# GO merge epilogue (full-mask units): gate and YA pieces of the later groups touched into L2 at epilogue entry; on top of v043
# baseline (speedup 1.0000x reference)
.LBB0_859:
	v_mov_b32_e32 v189, v239
	v_mov_b32_e32 v191, v241
	s_cmp_lt_i32 s85, 2
	s_mov_b64 s[0:1], -1
	s_cbranch_scc0 .LBB0_1183
	s_lshl_b32 s0, s75, 6
	s_add_i32 s0, s0, 0
	s_add_i32 s0, s0, 0x21400
	v_mov_b32_e32 v2, s0
	s_waitcnt lgkmcnt(0)
	ds_read_b96 v[134:136], v2
	v_mov_b32_e32 v2, s73
	ds_read_b32 v2, v2
	s_mov_b64 s[6:7], -1
	s_mov_b64 s[0:1], 0
	s_waitcnt lgkmcnt(0)
	v_readfirstlane_b32 s42, v134
	v_readfirstlane_b32 s36, v135
	v_readfirstlane_b32 s12, v2
	v_mov_b32_e32 v2, s77
	ds_read_b32 v2, v2
	v_readfirstlane_b32 s37, v136
	s_cmp_lt_i32 s42, 3
	s_mov_b64 s[14:15], 0
	s_waitcnt lgkmcnt(0)
	v_readfirstlane_b32 s13, v2
	s_cbranch_scc1 .LBB0_993
	s_cmp_gt_i32 s42, 3
	s_cbranch_scc0 .LBB0_966
	s_cmp_gt_i32 s42, 4
	s_cbranch_scc0 .LBB0_892
	s_cmp_eq_u32 s42, 5
	s_mov_b64 s[14:15], -1
	s_cbranch_scc0 .LBB0_891
	s_add_u32 s6, s12, 0x41900000
	s_addc_u32 s7, s13, 0
	s_add_u32 s8, s12, 0x2af00000
	s_addc_u32 s9, s13, 0
	s_cmp_eq_u32 s84, 0xff
	s_cbranch_scc0 .Lgo_notouch
	s_lshl_b32 s16, s4, 8
	v_readlane_b32 s17, v255, 18
	s_add_i32 s16, s16, s17
	v_add_u32_e32 v214, s16, v189
	s_lshl_b32 s16, s3, 8
	s_or_b32 s16, s16, s70
	v_lshl_add_u32 v215, v191, 3, s16
	v_lshlrev_b32_e32 v215, 1, v215
	v_lshl_add_u32 v216, v214, 12, v215
	v_mul_u32_u24_e32 v217, 0x3000, v214
	v_add_u32_e32 v217, v217, v215
	v_add_u32_e32 v217, 0x2000, v217
	s_add_u32 s16, s12, 0x3f500000
	s_addc_u32 s17, s13, 0
	global_load_dword v222, v216, s[16:17] offset:256
	global_load_dword v222, v217, s[8:9] offset:256
	v_add_u32_e32 v218, 0x10000, v216
	v_add_u32_e32 v219, 0x30000, v217
	global_load_dword v222, v218, s[16:17] offset:256
	global_load_dword v222, v219, s[8:9] offset:256
	v_add_u32_e32 v218, 0x20000, v216
	v_add_u32_e32 v219, 0x60000, v217
	global_load_dword v222, v218, s[16:17] offset:256
	global_load_dword v222, v219, s[8:9] offset:256
	v_add_u32_e32 v218, 0x30000, v216
	v_add_u32_e32 v219, 0x90000, v217
	global_load_dword v222, v218, s[16:17] offset:256
	global_load_dword v222, v219, s[8:9] offset:256
	v_add_u32_e32 v218, 0x80000, v216
	v_add_u32_e32 v219, 0x180000, v217
	global_load_dword v222, v218, s[16:17]
	global_load_dword v222, v219, s[8:9]
	global_load_dword v222, v218, s[16:17] offset:256
	global_load_dword v222, v219, s[8:9] offset:256
	v_add_u32_e32 v218, 0x90000, v216
	v_add_u32_e32 v219, 0x1b0000, v217
	global_load_dword v222, v218, s[16:17]
	global_load_dword v222, v219, s[8:9]
	global_load_dword v222, v218, s[16:17] offset:256
	global_load_dword v222, v219, s[8:9] offset:256
	v_add_u32_e32 v218, 0xa0000, v216
	v_add_u32_e32 v219, 0x1e0000, v217
	global_load_dword v222, v218, s[16:17]
	global_load_dword v222, v219, s[8:9]
	global_load_dword v222, v218, s[16:17] offset:256
	global_load_dword v222, v219, s[8:9] offset:256
	v_add_u32_e32 v218, 0xb0000, v216
	v_add_u32_e32 v219, 0x210000, v217
	global_load_dword v222, v218, s[16:17]
	global_load_dword v222, v219, s[8:9]
	global_load_dword v222, v218, s[16:17] offset:256
	global_load_dword v222, v219, s[8:9] offset:256
.Lgo_notouch:
	s_lshl_b32 s10, s4, 8
	v_readlane_b32 s11, v255, 18
	s_add_i32 s10, s10, s11
	v_add_u32_e32 v162, s10, v189
	s_lshl_b32 s10, s3, 8
	s_or_b32 s10, s10, s70
	v_lshl_add_u32 v4, v191, 3, s10
	v_ashrrev_i32_e32 v5, 31, v4
	v_lshlrev_b64 v[158:159], 1, v[4:5]
	v_lshl_add_u64 v[134:135], s[12:13], 0, v[158:159]
	s_mov_b64 s[10:11], 0x3f500000
	v_lshl_add_u64 v[160:161], v[134:135], 0, s[10:11]
	v_add_u32_e32 v134, 16, v162
	s_movk_i32 s14, 0x3000
	v_ashrrev_i32_e32 v135, 31, v134
	v_mov_b64_e32 v[136:137], s[8:9]
	v_mad_i64_i32 v[138:139], s[10:11], v134, s14, v[136:137]
	v_lshlrev_b64 v[168:169], 12, v[134:135]
	v_add_u32_e32 v134, 32, v162
	v_lshl_add_u64 v[176:177], v[138:139], 0, v[158:159]
	s_movk_i32 s15, 0x2000
	v_ashrrev_i32_e32 v135, 31, v134
	v_add_co_u32_e32 v138, vcc, s15, v176
	v_lshlrev_b64 v[166:167], 12, v[134:135]
	s_nop 0
	v_addc_co_u32_e32 v139, vcc, 0, v177, vcc
	v_lshl_add_u64 v[180:181], v[160:161], 0, v[166:167]
	global_load_dwordx4 v[150:153], v[138:139], off
	global_load_dwordx4 v[146:149], v[180:181], off
	v_mad_i64_i32 v[138:139], s[10:11], v134, s14, v[136:137]
	v_lshl_add_u64 v[178:179], v[138:139], 0, v[158:159]
	v_add_co_u32_e32 v138, vcc, s15, v178
	v_lshl_add_u64 v[174:175], v[160:161], 0, v[168:169]
	s_nop 0
	v_addc_co_u32_e32 v139, vcc, 0, v179, vcc
	global_load_dwordx4 v[142:145], v[138:139], off
	v_add_u32_e32 v138, 48, v162
	v_mad_i64_i32 v[134:135], s[10:11], v138, s14, v[136:137]
	v_ashrrev_i32_e32 v139, 31, v138
	v_lshl_add_u64 v[182:183], v[134:135], 0, v[158:159]
	v_add_co_u32_e32 v134, vcc, 0x2000, v182
	v_lshlrev_b64 v[164:165], 12, v[138:139]
	s_nop 0
	v_addc_co_u32_e32 v135, vcc, 0, v183, vcc
	v_lshl_add_u64 v[184:185], v[160:161], 0, v[164:165]
	global_load_dwordx4 v[154:157], v[174:175], off
	global_load_dwordx4 v[138:141], v[184:185], off
	v_mad_i64_i32 v[172:173], s[10:11], v162, s14, 0
	global_load_dwordx4 v[134:137], v[134:135], off
	s_and_b32 s14, s84, 1
	v_ashrrev_i32_e32 v163, 31, v162
	s_bitcmp1_b32 s84, 0
	v_lshlrev_b64 v[170:171], 12, v[162:163]
	s_cselect_b64 s[10:11], -1, 0
	s_cmp_eq_u32 s14, 0
	s_cbranch_scc1 .LBB0_866
	v_lshl_add_u64 v[186:187], v[160:161], 0, v[170:171]
	global_load_dwordx4 v[204:207], v[186:187], off
	v_lshl_add_u64 v[186:187], s[8:9], 0, v[172:173]
	v_lshl_add_u64 v[186:187], v[186:187], 0, v[158:159]
	v_add_co_u32_e32 v186, vcc, 0x2000, v186
	s_nop 1
	v_addc_co_u32_e32 v187, vcc, 0, v187, vcc
	global_load_dwordx4 v[208:211], v[186:187], off
	s_waitcnt vmcnt(0)
	v_lshlrev_b32_e32 v186, 16, v204
	v_and_b32_e32 v187, 0xffff0000, v204
	v_lshlrev_b32_e32 v204, 16, v205
	v_and_b32_e32 v205, 0xffff0000, v205
	v_lshlrev_b32_e32 v212, 16, v208
	v_and_b32_e32 v213, 0xffff0000, v208
	v_lshlrev_b32_e32 v208, 16, v209
	v_and_b32_e32 v209, 0xffff0000, v209
	v_pk_fma_f32 v[208:209], v[128:129], v[208:209], v[204:205]
	v_pk_fma_f32 v[186:187], v[126:127], v[212:213], v[186:187]
	v_lshlrev_b32_e32 v204, 16, v206
	v_and_b32_e32 v205, 0xffff0000, v206
	v_lshlrev_b32_e32 v206, 16, v207
	v_and_b32_e32 v207, 0xffff0000, v207
	v_lshlrev_b32_e32 v212, 16, v210
	v_and_b32_e32 v213, 0xffff0000, v210
	v_lshlrev_b32_e32 v210, 16, v211
	v_and_b32_e32 v211, 0xffff0000, v211
	v_pk_fma_f32 v[210:211], v[132:133], v[210:211], v[206:207]
	v_pk_fma_f32 v[206:207], v[130:131], v[212:213], v[204:205]
	v_cvt_pk_bf16_f32 v204, v186, v187
	v_lshl_add_u64 v[186:187], s[6:7], 0, v[170:171]
	v_cvt_pk_bf16_f32 v205, v208, v209
	v_cvt_pk_bf16_f32 v206, v206, v207
	v_cvt_pk_bf16_f32 v207, v210, v211
	v_lshl_add_u64 v[186:187], v[186:187], 0, v[158:159]
	global_store_dwordx4 v[186:187], v[204:207], off
